# prologue: waves 4-7 run both bf16 conversions first, then weight transposition item and W_eff
# baseline (speedup 1.0000x reference)
; DEVI const float* IN(int i) { return *(const float* const __attribute__((address_space(4)))*)(kargs() + 8 * i); }
; DEVI void prologue(int wv, LAS unsigned char* lds) {
;     ...
;     for (int it = gw; it < 2 * I_L; it += NGW) {
;         const int l = it / I_L; int r = it % I_L;
;         unsigned char* wl = ws + O_W + (size_t)l * W_LAYER;
;         if (r < I_IN) { const int kb = r / 101, nb = r % 101, n0 = nb * 32;
;             const int d0 = n0 < 384 ? n0 : n0 < 640 ? 512 + (n0 - 384) : n0 < 672 ? 384 + (n0 - 640) : n0 < 1184 ? 768 + (n0 - 672) : n0 < 2208 ? 1280 + (n0 - 1184) : 2304 + (n0 - 2208);
;             tr_item(IN(6) + (size_t)l * 1024 * 3232, 3232, 1024, IN(5) + l * 1024, (bf16_t*)(wl + W_IN), d0, scr, kb * 64, n0, lane); continue; }
.LBB0_23:
	s_or_b64 exec, exec, s[2:3]
	s_mov_b32 s16, s85
	s_mov_b32 s18, s95
	s_mov_b64 s[6:7], s[0:1]
	s_waitcnt lgkmcnt(0)
	s_mov_b32 s53, 0
	s_barrier
.Lpro_a:
	v_mbcnt_lo_u32_b32 v64, -1, 0
	v_mbcnt_hi_u32_b32 v64, -1, v64
	v_lshl_or_b32 v64, s33, 6, v64
	s_load_dwordx2 s[20:21], s[6:7], 0xb0
	v_readfirstlane_b32 s2, v64
	s_ashr_i32 s2, s2, 6
	s_lshl_b32 s3, s18, 3
	v_and_b32_e32 v34, 63, v64
	s_add_i32 s4, s3, s2
	s_lshl_b32 s14, s16, 3
	s_ashr_i32 s17, s16, 31
	v_ashrrev_i32_e32 v65, 31, v64
	s_movk_i32 s52, 0x35bf
	s_cmp_eq_u32 s16, 0x100
	s_cselect_b32 s52, 0x7ff, s52
	s_cmp_gt_i32 s4, s52
	v_lshlrev_b32_e32 v66, 3, v34
	s_cbranch_scc1 .LBB0_328
	s_bitcmp1_b32 s33, 2
	s_cbranch_scc0 .Lpro_a_go
	s_cmp_eq_u32 s53, 0
	s_cbranch_scc1 .LBB0_328
.Lpro_a_go:
	v_lshrrev_b32_e32 v0, 5, v34
	s_movk_i32 s3, 0x84
	v_mov_b32_e32 v1, 0x108
	v_mad_u32_u24 v13, v0, s3, v1
	v_mov_b32_e32 v1, 0x210
	v_mad_u32_u24 v15, v0, s3, v1
	v_mov_b32_e32 v1, 0x318
	v_mad_u32_u24 v17, v0, s3, v1
	v_mov_b32_e32 v1, 0x420
	v_mad_u32_u24 v19, v0, s3, v1
	v_mov_b32_e32 v1, 0x528
	v_mad_u32_u24 v21, v0, s3, v1
	v_mov_b32_e32 v1, 0x630
	v_mad_u32_u24 v23, v0, s3, v1
	v_mov_b32_e32 v1, 0x738
	v_mad_u32_u24 v25, v0, s3, v1
	v_mov_b32_e32 v1, 0x840
	v_mad_u32_u24 v27, v0, s3, v1
	v_mov_b32_e32 v1, 0x948
	v_mad_u32_u24 v29, v0, s3, v1
	v_mov_b32_e32 v1, 0xa50
	v_mad_u32_u24 v31, v0, s3, v1
	v_mov_b32_e32 v1, 0xb58
	v_mad_u32_u24 v33, v0, s3, v1
	v_mov_b32_e32 v1, 0xc60
	v_mad_u32_u24 v36, v0, s3, v1
	v_mov_b32_e32 v1, 0xd68
	v_mad_u32_u24 v38, v0, s3, v1
	v_mov_b32_e32 v1, 0xe70
	v_mad_u32_u24 v40, v0, s3, v1
	v_mov_b32_e32 v1, 0xf78
	v_mad_u32_u24 v42, v0, s3, v1
	v_mov_b32_e32 v1, 0x1080
	v_mad_u32_u24 v44, v0, s3, v1
	v_mov_b32_e32 v1, 0x1188
	v_mad_u32_u24 v46, v0, s3, v1
	v_mov_b32_e32 v1, 0x1290
	v_mad_u32_u24 v48, v0, s3, v1
	v_mov_b32_e32 v1, 0x1398
	v_mad_u32_u24 v50, v0, s3, v1
	v_mov_b32_e32 v1, 0x14a0
	v_mad_u32_u24 v51, v0, s3, v1
	v_mov_b32_e32 v1, 0x15a8
	v_mad_u32_u24 v52, v0, s3, v1
	v_mov_b32_e32 v1, 0x16b0
	s_mulk_i32 s2, 0x2100
	v_mad_u32_u24 v53, v0, s3, v1
	v_mov_b32_e32 v1, 0x17b8
	v_lshrrev_b32_e32 v55, 3, v34
	v_and_b32_e32 v6, 56, v66
	s_add_i32 s2, s2, 0
	v_mad_u32_u24 v54, v0, s3, v1
	v_mul_u32_u24_e32 v1, 0x84, v6
	v_lshlrev_b32_e32 v4, 2, v55
	s_waitcnt lgkmcnt(0)
	s_add_u32 s5, s20, 0x390800
	v_and_b32_e32 v2, 31, v64
	v_mov_b32_e32 v5, 0
	v_add3_u32 v56, s2, v1, v4
	v_mov_b32_e32 v1, 0x18c0
	s_mov_b32 s7, 0
	s_addc_u32 s15, s21, 0
	v_lshl_add_u32 v3, v2, 2, s2
	v_mul_u32_u24_e32 v7, 0x84, v0
	v_or_b32_e32 v12, 2, v0
	v_or_b32_e32 v14, 4, v0
	v_or_b32_e32 v16, 6, v0
	v_or_b32_e32 v18, 8, v0
	v_or_b32_e32 v20, 10, v0
	v_or_b32_e32 v22, 12, v0
	v_or_b32_e32 v24, 14, v0
	v_or_b32_e32 v26, 16, v0
	v_or_b32_e32 v28, 18, v0
	v_or_b32_e32 v30, 20, v0
	v_or_b32_e32 v32, 22, v0
	v_or_b32_e32 v35, 24, v0
	v_or_b32_e32 v37, 26, v0
	v_or_b32_e32 v39, 28, v0
	v_or_b32_e32 v41, 30, v0
	v_or_b32_e32 v43, 32, v0
	v_or_b32_e32 v45, 34, v0
	v_or_b32_e32 v47, 36, v0
	v_or_b32_e32 v49, 38, v0
	v_mad_u32_u24 v57, v0, s3, v1
	v_mov_b32_e32 v1, v5
	s_lshl_b32 s19, s4, 1
	s_lshl_b32 s40, s16, 4
	s_lshl_b32 s41, s4, 5
	s_lshl_b32 s42, s16, 8
	s_mov_b64 s[8:9], 0x1410000
	s_mov_b64 s[10:11], 0xc10000
	s_mov_b64 s[12:13], 0xa10000
	s_mov_b64 s[22:23], 0x810000
	s_movk_i32 s43, 0xf920
	s_movk_i32 s44, 0x300
	s_movk_i32 s45, 0xc00
	s_mov_b64 s[24:25], 0x680000
	s_mov_b32 s46, s4
	v_or_b32_e32 v58, 40, v0
	v_or_b32_e32 v59, 42, v0
	v_or_b32_e32 v60, 44, v0
	v_or_b32_e32 v61, 46, v0
	v_or_b32_e32 v62, 48, v0
	v_or_b32_e32 v63, 50, v0
	v_or_b32_e32 v67, 52, v0
	v_or_b32_e32 v68, 54, v0
	v_or_b32_e32 v69, 56, v0
	v_or_b32_e32 v70, 58, v0
	v_or_b32_e32 v71, 60, v0
	v_or_b32_e32 v72, 62, v0
	v_or_b32_e32 v73, 8, v55
	v_or_b32_e32 v74, 16, v55
	v_or_b32_e32 v75, 24, v55
	s_branch .LBB0_28

; DEVI const float* IN(int i) { return *(const float* const __attribute__((address_space(4)))*)(kargs() + 8 * i); }
; DEVI void prologue(int wv, LAS unsigned char* lds) {
;     ...
;     for (size_t i = gt; i < (size_t)2 * 96 * 1024 / 8; i += NGT) { const size_t l = i / (96 * 128), rem = i % (96 * 128);
;         *(u32x4*)(ws + O_W + l * W_LAYER + W_IN + ((size_t)416 * 1024) * 2 + rem * 16) = (u32x4){0u, 0u, 0u, 0u}; }
;     {
;         const float* wpool = IN(14); const float* pscale = IN(15); const float* wpo = IN(16);
;         for (size_t it = gt; it < (size_t)2 * 65536; it += NGT) {
.LBB0_331:
	s_or_b64 exec, exec, s[8:9]
	s_bitcmp1_b32 s33, 2
	s_cbranch_scc0 .Lpro_b
	s_cmp_eq_u32 s53, 0
	s_cbranch_scc1 .Lpro_c

; DEVI u32x4 pack8(const f32x4 a, const f32x4 b) { u32x4 w; w.x = cvtpk(a[0], a[1]); w.y = cvtpk(a[2], a[3]); w.z = cvtpk(b[0], b[1]); w.w = cvtpk(b[2], b[3]); return w; }
; DEVI void prologue(int wv, LAS unsigned char* lds) {
;     ...
;             for (int k = 0; k < 8; ++k) { const size_t ii = i + k * NGT; if (ii < (size_t)2 * MC * 256 / 8) *(u32x4*)(ckvb + ii * 8) = pack8(a[k], b[k]); }
;         }
;     }
;     { float* ssqz = (float*)(ws + O_SSQZ); for (size_t i = gt; i < SSQZ_FLOATS; i += NGT) ssqz[i] = 0.f; }
.LBB0_390:
	s_or_b64 exec, exec, s[26:27]
	s_bitcmp1_b32 s33, 2
	s_cbranch_scc0 .Lpro_e
	s_mov_b32 s53, 1
	s_mov_b32 s16, s85
	s_mov_b32 s18, s95
	s_mov_b64 s[6:7], s[0:1]
	s_branch .Lpro_a
.Lpro_e:
	s_mov_b64 s[2:3], 0xbae00
	v_cmp_gt_u64_e32 vcc, s[2:3], v[68:69]
	s_and_saveexec_b64 s[2:3], vcc
	s_cbranch_execz .LBB0_393
	s_lshl_b64 s[4:5], s[18:19], 11
	s_waitcnt lgkmcnt(0)
	s_add_u32 s4, s20, s4
	s_addc_u32 s5, s21, s5
	v_lshl_add_u64 v[0:1], v[64:65], 2, s[4:5]
	s_mov_b64 s[4:5], 0xa5000
	v_lshl_add_u64 v[0:1], v[0:1], 0, s[4:5]
	s_lshl_b64 s[4:5], s[16:17], 11
	s_mov_b64 s[6:7], 0
	v_mov_b32_e32 v2, 0
	s_mov_b64 s[8:9], 0xbadff
